# mixer C: 32-input row-max tree rewritten with 16 v_max3 (hipcc emitted 53 incl. canonicalising self-max); on top of pipelined LDS fragment reads
# speedup vs baseline: 1.0041x; 1.0041x over previous
.LBB0_580:
	s_nop 8
	v_max3_f32 v0, v80, v81, v82
	v_max3_f32 v2, v83, v84, v85
	v_max3_f32 v3, v86, v87, v88
	v_max3_f32 v4, v89, v90, v91
	v_max3_f32 v0, v0, v92, v93
	v_max3_f32 v2, v2, v94, v95
	v_max3_f32 v3, v3, v96, v97
	v_max3_f32 v4, v4, v98, v99
	v_max3_f32 v0, v0, v100, v101
	v_max3_f32 v2, v2, v102, v103
	v_max3_f32 v3, v3, v104, v105
	v_max3_f32 v4, v4, v106, v107
	v_max3_f32 v0, v0, v108, v109
	v_max3_f32 v2, v2, v110, v111
	v_max3_f32 v0, v0, v2, v3
	v_max_f32_e32 v0, v0, v4
	v_mov_b32_e32 v2, v0
	s_nop 1
	v_permlane32_swap_b32_e32 v0, v2
	v_max_f32_e32 v2, v2, v2
	v_max_f32_e32 v0, v0, v0
	v_max_f32_e32 v0, v0, v2
	v_cmp_lt_f32_e32 vcc, s22, v0
	s_cbranch_vccz .LBB0_566
	v_max_f32_e32 v0, v0, v0
	v_max_f32_e32 v0, 0, v0
	v_exp_f32_e64 v2, -v0
	v_pk_add_f32 v[80:81], v[80:81], v[0:1] op_sel_hi:[1,0] neg_lo:[0,1] neg_hi:[0,1]
	v_pk_add_f32 v[96:97], v[96:97], v[0:1] op_sel_hi:[1,0] neg_lo:[0,1] neg_hi:[0,1]
	v_pk_add_f32 v[82:83], v[82:83], v[0:1] op_sel_hi:[1,0] neg_lo:[0,1] neg_hi:[0,1]
	v_pk_add_f32 v[98:99], v[98:99], v[0:1] op_sel_hi:[1,0] neg_lo:[0,1] neg_hi:[0,1]
	v_pk_add_f32 v[84:85], v[84:85], v[0:1] op_sel_hi:[1,0] neg_lo:[0,1] neg_hi:[0,1]
	v_pk_add_f32 v[100:101], v[100:101], v[0:1] op_sel_hi:[1,0] neg_lo:[0,1] neg_hi:[0,1]
	v_pk_add_f32 v[86:87], v[86:87], v[0:1] op_sel_hi:[1,0] neg_lo:[0,1] neg_hi:[0,1]
	v_pk_add_f32 v[102:103], v[102:103], v[0:1] op_sel_hi:[1,0] neg_lo:[0,1] neg_hi:[0,1]
	v_pk_add_f32 v[88:89], v[88:89], v[0:1] op_sel_hi:[1,0] neg_lo:[0,1] neg_hi:[0,1]
	v_pk_add_f32 v[104:105], v[104:105], v[0:1] op_sel_hi:[1,0] neg_lo:[0,1] neg_hi:[0,1]
	v_pk_add_f32 v[90:91], v[90:91], v[0:1] op_sel_hi:[1,0] neg_lo:[0,1] neg_hi:[0,1]
	v_pk_add_f32 v[106:107], v[106:107], v[0:1] op_sel_hi:[1,0] neg_lo:[0,1] neg_hi:[0,1]
	v_pk_add_f32 v[92:93], v[92:93], v[0:1] op_sel_hi:[1,0] neg_lo:[0,1] neg_hi:[0,1]
	v_pk_add_f32 v[108:109], v[108:109], v[0:1] op_sel_hi:[1,0] neg_lo:[0,1] neg_hi:[0,1]
	v_pk_add_f32 v[94:95], v[94:95], v[0:1] op_sel_hi:[1,0] neg_lo:[0,1] neg_hi:[0,1]
	v_pk_add_f32 v[110:111], v[110:111], v[0:1] op_sel_hi:[1,0] neg_lo:[0,1] neg_hi:[0,1]
	v_add_f32_e32 v176, v176, v0
	v_pk_mul_f32 v[78:79], v[78:79], v[2:3] op_sel_hi:[1,0]
	v_pk_mul_f32 v[76:77], v[76:77], v[2:3] op_sel_hi:[1,0]
	v_pk_mul_f32 v[74:75], v[74:75], v[2:3] op_sel_hi:[1,0]
	v_pk_mul_f32 v[72:73], v[72:73], v[2:3] op_sel_hi:[1,0]
	v_pk_mul_f32 v[70:71], v[70:71], v[2:3] op_sel_hi:[1,0]
	v_pk_mul_f32 v[68:69], v[68:69], v[2:3] op_sel_hi:[1,0]
	v_pk_mul_f32 v[66:67], v[66:67], v[2:3] op_sel_hi:[1,0]
	v_pk_mul_f32 v[64:65], v[64:65], v[2:3] op_sel_hi:[1,0]
	v_pk_mul_f32 v[62:63], v[62:63], v[2:3] op_sel_hi:[1,0]
	v_pk_mul_f32 v[60:61], v[60:61], v[2:3] op_sel_hi:[1,0]
	v_pk_mul_f32 v[58:59], v[58:59], v[2:3] op_sel_hi:[1,0]
	v_pk_mul_f32 v[56:57], v[56:57], v[2:3] op_sel_hi:[1,0]
	v_pk_mul_f32 v[54:55], v[54:55], v[2:3] op_sel_hi:[1,0]
	v_pk_mul_f32 v[52:53], v[52:53], v[2:3] op_sel_hi:[1,0]
	v_pk_mul_f32 v[50:51], v[50:51], v[2:3] op_sel_hi:[1,0]
	v_pk_mul_f32 v[48:49], v[48:49], v[2:3] op_sel_hi:[1,0]
	v_pk_mul_f32 v[46:47], v[46:47], v[2:3] op_sel_hi:[1,0]
	v_pk_mul_f32 v[44:45], v[44:45], v[2:3] op_sel_hi:[1,0]
	v_pk_mul_f32 v[42:43], v[42:43], v[2:3] op_sel_hi:[1,0]
	v_pk_mul_f32 v[40:41], v[40:41], v[2:3] op_sel_hi:[1,0]
	v_pk_mul_f32 v[38:39], v[38:39], v[2:3] op_sel_hi:[1,0]
	v_pk_mul_f32 v[36:37], v[36:37], v[2:3] op_sel_hi:[1,0]
	v_pk_mul_f32 v[34:35], v[34:35], v[2:3] op_sel_hi:[1,0]
	v_pk_mul_f32 v[32:33], v[32:33], v[2:3] op_sel_hi:[1,0]
	v_pk_mul_f32 v[30:31], v[30:31], v[2:3] op_sel_hi:[1,0]
	v_pk_mul_f32 v[28:29], v[28:29], v[2:3] op_sel_hi:[1,0]
	v_pk_mul_f32 v[26:27], v[26:27], v[2:3] op_sel_hi:[1,0]
	v_pk_mul_f32 v[24:25], v[24:25], v[2:3] op_sel_hi:[1,0]
	v_pk_mul_f32 v[22:23], v[22:23], v[2:3] op_sel_hi:[1,0]
	v_pk_mul_f32 v[20:21], v[20:21], v[2:3] op_sel_hi:[1,0]
	v_pk_mul_f32 v[18:19], v[18:19], v[2:3] op_sel_hi:[1,0]
	v_pk_mul_f32 v[16:17], v[16:17], v[2:3] op_sel_hi:[1,0]
	v_mul_f32_e32 v194, v194, v2
	s_branch .LBB0_566

.LBB0_610:
	s_nop 6
	v_max3_f32 v0, v80, v81, v82
	v_max3_f32 v2, v83, v84, v85
	v_max3_f32 v3, v86, v87, v88
	v_max3_f32 v4, v89, v90, v91
	v_max3_f32 v0, v0, v92, v93
	v_max3_f32 v2, v2, v94, v95
	v_max3_f32 v3, v3, v96, v97
	v_max3_f32 v4, v4, v98, v99
	v_max3_f32 v0, v0, v100, v101
	v_max3_f32 v2, v2, v102, v103
	v_max3_f32 v3, v3, v104, v105
	v_max3_f32 v4, v4, v106, v107
	v_max3_f32 v0, v0, v108, v109
	v_max3_f32 v2, v2, v110, v111
	v_max3_f32 v0, v0, v2, v3
	v_max_f32_e32 v0, v0, v4
	v_mov_b32_e32 v2, v0
	s_nop 1
	v_permlane32_swap_b32_e32 v0, v2
	s_waitcnt lgkmcnt(0)
	s_barrier
	v_max_f32_e32 v2, v2, v2
	v_max_f32_e32 v0, v0, v0
	v_max_f32_e32 v0, v0, v2
	v_cmp_lt_f32_e32 vcc, s22, v0
	s_cbranch_vccz .LBB0_612
	v_max_f32_e32 v0, v0, v0
	v_max_f32_e32 v0, 0, v0
	v_exp_f32_e64 v2, -v0
	v_pk_add_f32 v[80:81], v[80:81], v[0:1] op_sel_hi:[1,0] neg_lo:[0,1] neg_hi:[0,1]
	v_pk_add_f32 v[96:97], v[96:97], v[0:1] op_sel_hi:[1,0] neg_lo:[0,1] neg_hi:[0,1]
	v_pk_add_f32 v[82:83], v[82:83], v[0:1] op_sel_hi:[1,0] neg_lo:[0,1] neg_hi:[0,1]
	v_pk_mul_f32 v[78:79], v[78:79], v[2:3] op_sel_hi:[1,0]
	v_pk_mul_f32 v[76:77], v[76:77], v[2:3] op_sel_hi:[1,0]
	v_pk_mul_f32 v[74:75], v[74:75], v[2:3] op_sel_hi:[1,0]
	v_pk_mul_f32 v[72:73], v[72:73], v[2:3] op_sel_hi:[1,0]
	v_pk_mul_f32 v[70:71], v[70:71], v[2:3] op_sel_hi:[1,0]
	v_pk_mul_f32 v[68:69], v[68:69], v[2:3] op_sel_hi:[1,0]
	v_pk_mul_f32 v[66:67], v[66:67], v[2:3] op_sel_hi:[1,0]
	v_pk_mul_f32 v[64:65], v[64:65], v[2:3] op_sel_hi:[1,0]
	v_pk_mul_f32 v[62:63], v[62:63], v[2:3] op_sel_hi:[1,0]
	v_pk_mul_f32 v[60:61], v[60:61], v[2:3] op_sel_hi:[1,0]
	v_pk_mul_f32 v[58:59], v[58:59], v[2:3] op_sel_hi:[1,0]
	v_pk_mul_f32 v[56:57], v[56:57], v[2:3] op_sel_hi:[1,0]
	v_pk_mul_f32 v[54:55], v[54:55], v[2:3] op_sel_hi:[1,0]
	v_pk_mul_f32 v[52:53], v[52:53], v[2:3] op_sel_hi:[1,0]
	v_pk_mul_f32 v[50:51], v[50:51], v[2:3] op_sel_hi:[1,0]
	v_pk_mul_f32 v[48:49], v[48:49], v[2:3] op_sel_hi:[1,0]
	v_pk_mul_f32 v[46:47], v[46:47], v[2:3] op_sel_hi:[1,0]
	v_pk_mul_f32 v[44:45], v[44:45], v[2:3] op_sel_hi:[1,0]
	v_pk_mul_f32 v[42:43], v[42:43], v[2:3] op_sel_hi:[1,0]
	v_pk_mul_f32 v[40:41], v[40:41], v[2:3] op_sel_hi:[1,0]
	v_pk_mul_f32 v[38:39], v[38:39], v[2:3] op_sel_hi:[1,0]
	v_pk_mul_f32 v[36:37], v[36:37], v[2:3] op_sel_hi:[1,0]
	v_pk_mul_f32 v[34:35], v[34:35], v[2:3] op_sel_hi:[1,0]
	v_pk_mul_f32 v[32:33], v[32:33], v[2:3] op_sel_hi:[1,0]
	v_pk_mul_f32 v[30:31], v[30:31], v[2:3] op_sel_hi:[1,0]
	v_pk_mul_f32 v[28:29], v[28:29], v[2:3] op_sel_hi:[1,0]
	v_pk_mul_f32 v[26:27], v[26:27], v[2:3] op_sel_hi:[1,0]
	v_pk_mul_f32 v[24:25], v[24:25], v[2:3] op_sel_hi:[1,0]
	v_pk_mul_f32 v[22:23], v[22:23], v[2:3] op_sel_hi:[1,0]
	v_pk_mul_f32 v[20:21], v[20:21], v[2:3] op_sel_hi:[1,0]
	v_pk_mul_f32 v[18:19], v[18:19], v[2:3] op_sel_hi:[1,0]
	v_pk_mul_f32 v[16:17], v[16:17], v[2:3] op_sel_hi:[1,0]
	v_mov_b32_e32 v3, v0
	v_pk_add_f32 v[4:5], v[194:195], v[2:3]
	v_pk_mul_f32 v[194:195], v[194:195], v[2:3]
	v_pk_add_f32 v[98:99], v[98:99], v[0:1] op_sel_hi:[1,0] neg_lo:[0,1] neg_hi:[0,1]
	v_pk_add_f32 v[84:85], v[84:85], v[0:1] op_sel_hi:[1,0] neg_lo:[0,1] neg_hi:[0,1]
	v_pk_add_f32 v[100:101], v[100:101], v[0:1] op_sel_hi:[1,0] neg_lo:[0,1] neg_hi:[0,1]
	v_pk_add_f32 v[86:87], v[86:87], v[0:1] op_sel_hi:[1,0] neg_lo:[0,1] neg_hi:[0,1]
	v_pk_add_f32 v[102:103], v[102:103], v[0:1] op_sel_hi:[1,0] neg_lo:[0,1] neg_hi:[0,1]
	v_pk_add_f32 v[88:89], v[88:89], v[0:1] op_sel_hi:[1,0] neg_lo:[0,1] neg_hi:[0,1]
	v_pk_add_f32 v[104:105], v[104:105], v[0:1] op_sel_hi:[1,0] neg_lo:[0,1] neg_hi:[0,1]
	v_pk_add_f32 v[90:91], v[90:91], v[0:1] op_sel_hi:[1,0] neg_lo:[0,1] neg_hi:[0,1]
	v_pk_add_f32 v[106:107], v[106:107], v[0:1] op_sel_hi:[1,0] neg_lo:[0,1] neg_hi:[0,1]
	v_pk_add_f32 v[92:93], v[92:93], v[0:1] op_sel_hi:[1,0] neg_lo:[0,1] neg_hi:[0,1]
	v_pk_add_f32 v[108:109], v[108:109], v[0:1] op_sel_hi:[1,0] neg_lo:[0,1] neg_hi:[0,1]
	v_pk_add_f32 v[94:95], v[94:95], v[0:1] op_sel_hi:[1,0] neg_lo:[0,1] neg_hi:[0,1]
	v_pk_add_f32 v[110:111], v[110:111], v[0:1] op_sel_hi:[1,0] neg_lo:[0,1] neg_hi:[0,1]
	v_mov_b32_e32 v195, v5
